# v20 + accumulator zeroing in front of every GEMM K-loop: 128 v_mov_b32 -> 64 v_mov_b64 (8 sites)
# baseline (speedup 1.0000x reference)
; template <class Epi, class Sched, bool ALIGN_EPI = false, bool SP2 = false>
; __device__ __forceinline__ void gemm_phase(PG8_LAS unsigned char* lds, const Gemm g, const Sched& S, const Epi& E) {
;     ...
;         const bool has_next = S.next(ui + 1, nxt);
;         const char* nA = has_next ? (const char*)g.A + (size_t)nxt.pm * tstep : cA; const char* nB = has_next ? (const char*)g.Bt + (size_t)nxt.pn * tstep : cB;
;         for (int t = 0; t < nt; t += 2) {
;             const bool last = (t == nt - 2);
;             const char* a1 = cA + (size_t)(t + 1) * kstep;
;             const char* a2 = last ? nA : cA + (size_t)(t + 2) * kstep; const char* b2 = last ? nB : cB + (size_t)(t + 2) * kstep;
;             const char* a3 = a2 + kstep; const char* b3 = b2 + kstep;
;     ...
; #pragma unroll
;         for (int a = 0; a < 2; ++a)
; #pragma unroll
;             for (int b = 0; b < 2; ++b)
; #pragma unroll
;                 for (int m = 0; m < 4; ++m)
; #pragma unroll
;                     for (int n = 0; n < 2; ++n) acc[a][b][m][n] = (f32x4){0.f, 0.f, 0.f, 0.f};
;         cur = nxt; cA = nA; cB = nB; ++ui;
.LBB0_509:
	s_ashr_i32 s57, s56, 31
	s_lshl_b64 s[58:59], s[56:57], 19
	s_add_u32 s58, s28, s58
	s_addc_u32 s59, s29, s59
	s_and_b64 s[60:61], s[8:9], exec
	s_cselect_b32 s57, s59, s67
	s_cselect_b32 s63, s58, s66
	s_ashr_i32 s55, s54, 31
	s_lshl_b64 s[60:61], s[54:55], 19
	s_add_u32 s60, s33, s60
	s_addc_u32 s61, s70, s61
	s_and_b64 s[68:69], s[8:9], exec
	s_cselect_b32 s55, s61, s11
	s_cselect_b32 s95, s60, s10
	s_add_u32 s96, s10, 0x100
	s_addc_u32 s97, s11, 0
	s_add_u32 s10, s66, 0x40080
	v_mov_b64_e32 v[0:1], 0
	v_mov_b64_e32 v[2:3], 0
	v_mov_b64_e32 v[4:5], 0
	v_mov_b64_e32 v[6:7], 0
	v_mov_b64_e32 v[8:9], 0
	v_mov_b64_e32 v[10:11], 0
	v_mov_b64_e32 v[12:13], 0
	v_mov_b64_e32 v[14:15], 0
	v_mov_b64_e32 v[16:17], 0
	v_mov_b64_e32 v[18:19], 0
	v_mov_b64_e32 v[20:21], 0
	v_mov_b64_e32 v[22:23], 0
	v_mov_b64_e32 v[24:25], 0
	v_mov_b64_e32 v[26:27], 0
	v_mov_b64_e32 v[28:29], 0
	v_mov_b64_e32 v[30:31], 0
	v_mov_b64_e32 v[32:33], 0
	v_mov_b64_e32 v[34:35], 0
	v_mov_b64_e32 v[36:37], 0
	v_mov_b64_e32 v[38:39], 0
	v_mov_b64_e32 v[40:41], 0
	v_mov_b64_e32 v[42:43], 0
	v_mov_b64_e32 v[44:45], 0
	v_mov_b64_e32 v[46:47], 0
	v_mov_b64_e32 v[48:49], 0
	v_mov_b64_e32 v[50:51], 0
	v_mov_b64_e32 v[52:53], 0
	v_mov_b64_e32 v[54:55], 0
	v_mov_b64_e32 v[56:57], 0
	v_mov_b64_e32 v[58:59], 0
	v_mov_b64_e32 v[60:61], 0
	v_mov_b64_e32 v[62:63], 0
	v_mov_b64_e32 v[64:65], 0
	v_mov_b64_e32 v[66:67], 0
	v_mov_b64_e32 v[68:69], 0
	v_mov_b64_e32 v[70:71], 0
	v_mov_b64_e32 v[72:73], 0
	v_mov_b64_e32 v[74:75], 0
	v_mov_b64_e32 v[76:77], 0
	v_mov_b64_e32 v[78:79], 0
	v_mov_b64_e32 v[80:81], 0
	v_mov_b64_e32 v[82:83], 0
	v_mov_b64_e32 v[84:85], 0
	v_mov_b64_e32 v[86:87], 0
	v_mov_b64_e32 v[88:89], 0
	v_mov_b64_e32 v[90:91], 0
	v_mov_b64_e32 v[92:93], 0
	v_mov_b64_e32 v[94:95], 0
	v_mov_b64_e32 v[96:97], 0
	v_mov_b64_e32 v[98:99], 0
	v_mov_b64_e32 v[100:101], 0
	v_mov_b64_e32 v[102:103], 0
	v_mov_b64_e32 v[104:105], 0
	v_mov_b64_e32 v[106:107], 0
	v_mov_b64_e32 v[108:109], 0
	v_mov_b64_e32 v[110:111], 0
	v_mov_b64_e32 v[112:113], 0
	v_mov_b64_e32 v[114:115], 0
	v_mov_b64_e32 v[116:117], 0
	v_mov_b64_e32 v[118:119], 0
	v_mov_b64_e32 v[120:121], 0
	v_mov_b64_e32 v[122:123], 0
	v_mov_b64_e32 v[124:125], 0
	v_mov_b64_e32 v[126:127], 0
	s_addc_u32 s11, s67, 0
	s_mov_b32 vcc_lo, -2

; template <class Epi, class Sched, bool ALIGN_EPI = false, bool SP2 = false>
; __device__ __forceinline__ void gemm_phase(PG8_LAS unsigned char* lds, const Gemm g, const Sched& S, const Epi& E) {
;     ...
;         const bool has_next = S.next(ui + 1, nxt);
;         const char* nA = has_next ? (const char*)g.A + (size_t)nxt.pm * tstep : cA; const char* nB = has_next ? (const char*)g.Bt + (size_t)nxt.pn * tstep : cB;
;         for (int t = 0; t < nt; t += 2) {
;             const bool last = (t == nt - 2);
;             const char* a1 = cA + (size_t)(t + 1) * kstep;
;             const char* a2 = last ? nA : cA + (size_t)(t + 2) * kstep; const char* b2 = last ? nB : cB + (size_t)(t + 2) * kstep;
;             const char* a3 = a2 + kstep; const char* b3 = b2 + kstep;
;     ...
; #pragma unroll
;         for (int a = 0; a < 2; ++a)
; #pragma unroll
;             for (int b = 0; b < 2; ++b)
; #pragma unroll
;                 for (int m = 0; m < 4; ++m)
; #pragma unroll
;                     for (int n = 0; n < 2; ++n) acc[a][b][m][n] = (f32x4){0.f, 0.f, 0.f, 0.f};
;         cur = nxt; cA = nA; cB = nB; ++ui;
.LBB0_709:
	s_ashr_i32 s45, s44, 31
	s_lshl_b64 s[34:35], s[44:45], 19
	s_add_u32 s46, s33, s34
	s_addc_u32 s47, s60, s35
	s_and_b64 s[34:35], s[8:9], exec
	s_cselect_b32 s45, s47, s57
	s_cselect_b32 s51, s46, s56
	s_ashr_i32 s43, s42, 31
	s_lshl_b64 s[34:35], s[42:43], 19
	s_add_u32 s48, s61, s34
	s_addc_u32 s49, s62, s35
	s_and_b64 s[34:35], s[8:9], exec
	s_cselect_b32 s43, s49, s55
	s_cselect_b32 s53, s48, s54
	s_add_u32 s82, s54, 0x100
	s_addc_u32 s83, s55, 0
	s_add_u32 s54, s56, 0x40080
	v_mov_b64_e32 v[0:1], 0
	v_mov_b64_e32 v[2:3], 0
	v_mov_b64_e32 v[4:5], 0
	v_mov_b64_e32 v[6:7], 0
	v_mov_b64_e32 v[8:9], 0
	v_mov_b64_e32 v[10:11], 0
	v_mov_b64_e32 v[12:13], 0
	v_mov_b64_e32 v[14:15], 0
	v_mov_b64_e32 v[16:17], 0
	v_mov_b64_e32 v[18:19], 0
	v_mov_b64_e32 v[20:21], 0
	v_mov_b64_e32 v[22:23], 0
	v_mov_b64_e32 v[24:25], 0
	v_mov_b64_e32 v[26:27], 0
	v_mov_b64_e32 v[28:29], 0
	v_mov_b64_e32 v[30:31], 0
	v_mov_b64_e32 v[32:33], 0
	v_mov_b64_e32 v[34:35], 0
	v_mov_b64_e32 v[36:37], 0
	v_mov_b64_e32 v[38:39], 0
	v_mov_b64_e32 v[40:41], 0
	v_mov_b64_e32 v[42:43], 0
	v_mov_b64_e32 v[44:45], 0
	v_mov_b64_e32 v[46:47], 0
	v_mov_b64_e32 v[48:49], 0
	v_mov_b64_e32 v[50:51], 0
	v_mov_b64_e32 v[52:53], 0
	v_mov_b64_e32 v[54:55], 0
	v_mov_b64_e32 v[56:57], 0
	v_mov_b64_e32 v[58:59], 0
	v_mov_b64_e32 v[60:61], 0
	v_mov_b64_e32 v[62:63], 0
	v_mov_b64_e32 v[64:65], 0
	v_mov_b64_e32 v[66:67], 0
	v_mov_b64_e32 v[68:69], 0
	v_mov_b64_e32 v[70:71], 0
	v_mov_b64_e32 v[72:73], 0
	v_mov_b64_e32 v[74:75], 0
	v_mov_b64_e32 v[76:77], 0
	v_mov_b64_e32 v[78:79], 0
	v_mov_b64_e32 v[80:81], 0
	v_mov_b64_e32 v[82:83], 0
	v_mov_b64_e32 v[84:85], 0
	v_mov_b64_e32 v[86:87], 0
	v_mov_b64_e32 v[88:89], 0
	v_mov_b64_e32 v[90:91], 0
	v_mov_b64_e32 v[92:93], 0
	v_mov_b64_e32 v[94:95], 0
	v_mov_b64_e32 v[96:97], 0
	v_mov_b64_e32 v[98:99], 0
	v_mov_b64_e32 v[100:101], 0
	v_mov_b64_e32 v[102:103], 0
	v_mov_b64_e32 v[104:105], 0
	v_mov_b64_e32 v[106:107], 0
	v_mov_b64_e32 v[108:109], 0
	v_mov_b64_e32 v[110:111], 0
	v_mov_b64_e32 v[112:113], 0
	v_mov_b64_e32 v[114:115], 0
	v_mov_b64_e32 v[116:117], 0
	v_mov_b64_e32 v[118:119], 0
	v_mov_b64_e32 v[120:121], 0
	v_mov_b64_e32 v[122:123], 0
	v_mov_b64_e32 v[124:125], 0
	v_mov_b64_e32 v[126:127], 0
	s_addc_u32 s55, s57, 0
	s_mov_b32 s84, -2
	s_waitcnt lgkmcnt(0)

; #define PG8_LAS __attribute__((address_space(3)))
;     __device__ __forceinline__ void prefetch(PG8_LAS unsigned char* sp, const Unit& u, int wid, int lane) const {
;         const int seq = (u.pm < 256) ? (u.pm >> 3) : 32;
;         const float* src = (wid < 4) ? rowss + u.pm * BM + wid * 64 : bias + (size_t)seq * 5632 + u.pn * HALF + (wid < 6 ? (wid - 4) * 64 : 2816 + (wid - 6) * 64);
;         __builtin_amdgcn_global_load_lds((const unsigned*)(src + lane), (PG8_LAS unsigned*)(sp + wid * 256), 4, 0, 0);
; template <class Epi, class Sched, bool ALIGN_EPI = false, bool SP2 = false>
; __device__ __forceinline__ void gemm_phase(PG8_LAS unsigned char* lds, const Gemm g, const Sched& S, const Epi& E) {
;     ...
; #pragma unroll
;         for (int a = 0; a < 2; ++a)
; #pragma unroll
;             for (int b = 0; b < 2; ++b)
; #pragma unroll
;                 for (int m = 0; m < 4; ++m)
; #pragma unroll
;                     for (int n = 0; n < 2; ++n) acc[a][b][m][n] = (f32x4){0.f, 0.f, 0.f, 0.f};
;         cur = nxt; cA = nA; cB = nB; ++ui;
.LBB0_795:
	s_ashr_i32 s43, s42, 31
	s_lshl_b64 s[34:35], s[42:43], 19
	s_add_u32 s44, s28, s34
	s_addc_u32 s45, s29, s35
	s_and_b64 s[34:35], s[6:7], exec
	s_cselect_b32 s43, s45, s57
	s_cselect_b32 s78, s44, s56
	s_ashr_i32 s41, s40, 31
	s_lshl_b64 s[34:35], s[40:41], 19
	s_add_u32 s46, s33, s34
	s_addc_u32 s47, s58, s35
	s_and_b64 s[34:35], s[6:7], exec
	s_cselect_b32 s41, s47, s53
	s_cselect_b32 s79, s46, s52
	s_lshl_b32 s48, s48, 7
	s_lshl_b32 s50, s54, 8
	s_ashr_i32 s12, s54, 3
	s_ashr_i32 s49, s48, 31
	s_ashr_i32 s51, s50, 31
	s_cmpk_lt_i32 s54, 0x100
	s_mul_i32 s13, s12, 0x1600
	s_mul_hi_i32 s12, s12, 0x1600
	s_cselect_b32 s35, s12, 0
	s_cselect_b32 s34, s13, 0x2c000
	s_lshl_b64 s[34:35], s[34:35], 2
	s_add_u32 s12, s66, s34
	s_addc_u32 s13, s67, s35
	s_lshl_b64 s[34:35], s[48:49], 2
	s_add_u32 s12, s12, s34
	s_addc_u32 s13, s13, s35
	s_add_u32 s12, s12, s10
	s_addc_u32 s13, s13, s11
	s_lshl_b64 s[34:35], s[50:51], 2
	s_add_u32 s14, s73, s34
	s_addc_u32 s15, s74, s35
	s_and_b64 s[34:35], s[22:23], exec
	s_cselect_b32 s35, s15, s13
	s_cselect_b32 s34, s14, s12
	s_add_u32 s49, s52, 0x100
	s_addc_u32 s51, s53, 0
	s_add_u32 s52, s56, 0x40080
	v_mov_b64_e32 v[0:1], 0
	v_mov_b64_e32 v[2:3], 0
	v_mov_b64_e32 v[4:5], 0
	v_mov_b64_e32 v[6:7], 0
	v_mov_b64_e32 v[8:9], 0
	v_mov_b64_e32 v[10:11], 0
	v_mov_b64_e32 v[12:13], 0
	v_mov_b64_e32 v[14:15], 0
	v_mov_b64_e32 v[16:17], 0
	v_mov_b64_e32 v[18:19], 0
	v_mov_b64_e32 v[20:21], 0
	v_mov_b64_e32 v[22:23], 0
	v_mov_b64_e32 v[24:25], 0
	v_mov_b64_e32 v[26:27], 0
	v_mov_b64_e32 v[28:29], 0
	v_mov_b64_e32 v[30:31], 0
	v_mov_b64_e32 v[32:33], 0
	v_mov_b64_e32 v[34:35], 0
	v_mov_b64_e32 v[36:37], 0
	v_mov_b64_e32 v[38:39], 0
	v_mov_b64_e32 v[40:41], 0
	v_mov_b64_e32 v[42:43], 0
	v_mov_b64_e32 v[44:45], 0
	v_mov_b64_e32 v[46:47], 0
	v_mov_b64_e32 v[48:49], 0
	v_mov_b64_e32 v[50:51], 0
	v_mov_b64_e32 v[52:53], 0
	v_mov_b64_e32 v[54:55], 0
	v_mov_b64_e32 v[56:57], 0
	v_mov_b64_e32 v[58:59], 0
	v_mov_b64_e32 v[60:61], 0
	v_mov_b64_e32 v[62:63], 0
	v_mov_b64_e32 v[64:65], 0
	v_mov_b64_e32 v[66:67], 0
	v_mov_b64_e32 v[68:69], 0
	v_mov_b64_e32 v[70:71], 0
	v_mov_b64_e32 v[72:73], 0
	v_mov_b64_e32 v[74:75], 0
	v_mov_b64_e32 v[76:77], 0
	v_mov_b64_e32 v[78:79], 0
	v_mov_b64_e32 v[80:81], 0
	v_mov_b64_e32 v[82:83], 0
	v_mov_b64_e32 v[84:85], 0
	v_mov_b64_e32 v[86:87], 0
	v_mov_b64_e32 v[88:89], 0
	v_mov_b64_e32 v[90:91], 0
	v_mov_b64_e32 v[92:93], 0
	v_mov_b64_e32 v[94:95], 0
	v_mov_b64_e32 v[96:97], 0
	v_mov_b64_e32 v[98:99], 0
	v_mov_b64_e32 v[100:101], 0
	v_mov_b64_e32 v[102:103], 0
	v_mov_b64_e32 v[104:105], 0
	v_mov_b64_e32 v[106:107], 0
	v_mov_b64_e32 v[108:109], 0
	v_mov_b64_e32 v[110:111], 0
	v_mov_b64_e32 v[112:113], 0
	v_mov_b64_e32 v[114:115], 0
	v_mov_b64_e32 v[132:133], 0
	v_mov_b64_e32 v[134:135], 0
	v_mov_b64_e32 v[136:137], 0
	v_mov_b64_e32 v[138:139], 0
	v_mov_b64_e32 v[140:141], 0
	v_mov_b64_e32 v[142:143], 0
	v_lshl_add_u64 v[116:117], s[34:35], 0, v[162:163]
	s_addc_u32 s53, s57, 0
	s_mov_b32 s80, -2
	s_branch .LBB0_797

; template <class Epi, class Sched, bool ALIGN_EPI = false, bool SP2 = false>
; __device__ __forceinline__ void gemm_phase(PG8_LAS unsigned char* lds, const Gemm g, const Sched& S, const Epi& E) {
;     ...
;             const char* a1 = cA + (size_t)(t + 1) * kstep;
;             const char* a2 = last ? nA : cA + (size_t)(t + 2) * kstep; const char* b2 = last ? nB : cB + (size_t)(t + 2) * kstep;
;     ...
; #pragma unroll
;         for (int a = 0; a < 2; ++a)
; #pragma unroll
;             for (int b = 0; b < 2; ++b)
; #pragma unroll
;                 for (int m = 0; m < 4; ++m)
; #pragma unroll
;                     for (int n = 0; n < 2; ++n) acc[a][b][m][n] = (f32x4){0.f, 0.f, 0.f, 0.f};
;         cur = nxt; cA = nA; cB = nB; ++ui;
.LBB0_871:
	s_add_u32 s71, s42, 0x100
	v_mov_b64_e32 v[0:1], 0
	v_mov_b64_e32 v[2:3], 0
	v_mov_b64_e32 v[4:5], 0
	v_mov_b64_e32 v[6:7], 0
	v_mov_b64_e32 v[8:9], 0
	v_mov_b64_e32 v[10:11], 0
	v_mov_b64_e32 v[12:13], 0
	v_mov_b64_e32 v[14:15], 0
	v_mov_b64_e32 v[16:17], 0
	v_mov_b64_e32 v[18:19], 0
	v_mov_b64_e32 v[20:21], 0
	v_mov_b64_e32 v[22:23], 0
	v_mov_b64_e32 v[24:25], 0
	v_mov_b64_e32 v[26:27], 0
	v_mov_b64_e32 v[28:29], 0
	v_mov_b64_e32 v[30:31], 0
	v_mov_b64_e32 v[32:33], 0
	v_mov_b64_e32 v[34:35], 0
	v_mov_b64_e32 v[36:37], 0
	v_mov_b64_e32 v[38:39], 0
	v_mov_b64_e32 v[40:41], 0
	v_mov_b64_e32 v[42:43], 0
	v_mov_b64_e32 v[44:45], 0
	v_mov_b64_e32 v[46:47], 0
	v_mov_b64_e32 v[48:49], 0
	v_mov_b64_e32 v[50:51], 0
	v_mov_b64_e32 v[52:53], 0
	v_mov_b64_e32 v[54:55], 0
	v_mov_b64_e32 v[56:57], 0
	v_mov_b64_e32 v[58:59], 0
	v_mov_b64_e32 v[60:61], 0
	v_mov_b64_e32 v[62:63], 0
	v_mov_b64_e32 v[64:65], 0
	v_mov_b64_e32 v[66:67], 0
	v_mov_b64_e32 v[68:69], 0
	v_mov_b64_e32 v[70:71], 0
	v_mov_b64_e32 v[72:73], 0
	v_mov_b64_e32 v[74:75], 0
	v_mov_b64_e32 v[76:77], 0
	v_mov_b64_e32 v[78:79], 0
	v_mov_b64_e32 v[80:81], 0
	v_mov_b64_e32 v[82:83], 0
	v_mov_b64_e32 v[84:85], 0
	v_mov_b64_e32 v[86:87], 0
	v_mov_b64_e32 v[88:89], 0
	v_mov_b64_e32 v[90:91], 0
	v_mov_b64_e32 v[92:93], 0
	v_mov_b64_e32 v[94:95], 0
	v_mov_b64_e32 v[96:97], 0
	v_mov_b64_e32 v[98:99], 0
	v_mov_b64_e32 v[100:101], 0
	v_mov_b64_e32 v[102:103], 0
	v_mov_b64_e32 v[104:105], 0
	v_mov_b64_e32 v[106:107], 0
	v_mov_b64_e32 v[108:109], 0
	v_mov_b64_e32 v[110:111], 0
	v_mov_b64_e32 v[112:113], 0
	v_mov_b64_e32 v[114:115], 0
	v_mov_b64_e32 v[116:117], 0
	v_mov_b64_e32 v[118:119], 0
	v_mov_b64_e32 v[120:121], 0
	v_mov_b64_e32 v[122:123], 0
	v_mov_b64_e32 v[124:125], 0
	v_mov_b64_e32 v[126:127], 0
	s_addc_u32 s73, s43, 0
	s_mov_b32 s74, -2
	s_waitcnt lgkmcnt(0)

; #define PG8_LAS __attribute__((address_space(3)))
;     __device__ __forceinline__ void prefetch(PG8_LAS unsigned char* sp, const Unit& u, int wid, int lane) const {
;         if (PRE) { const int seq = (u.pm < 256) ? (u.pm >> 3) : 32;
;             const float* src = (wid < 4) ? rowss + u.pm * BM + wid * 64 : bias + (size_t)seq * N + u.pn * BM + (wid - 4) * 64;
;             __builtin_amdgcn_global_load_lds((const unsigned*)(src + lane), (PG8_LAS unsigned*)(sp + wid * 256), 4, 0, 0); }
;     }
; template <class Epi, class Sched, bool ALIGN_EPI = false, bool SP2 = false>
; __device__ __forceinline__ void gemm_phase(PG8_LAS unsigned char* lds, const Gemm g, const Sched& S, const Epi& E) {
;     ...
; #pragma unroll
;         for (int a = 0; a < 2; ++a)
; #pragma unroll
;             for (int b = 0; b < 2; ++b)
; #pragma unroll
;                 for (int m = 0; m < 4; ++m)
; #pragma unroll
;                     for (int n = 0; n < 2; ++n) acc[a][b][m][n] = (f32x4){0.f, 0.f, 0.f, 0.f};
;         cur = nxt; cA = nA; cB = nB; ++ui;
.LBB0_959:
	s_ashr_i32 s57, s56, 31
	s_lshl_b64 s[58:59], s[56:57], 19
	s_add_u32 s58, s34, s58
	s_addc_u32 s59, s35, s59
	s_and_b64 s[60:61], s[8:9], exec
	s_cselect_b32 s57, s59, s69
	s_cselect_b32 s63, s58, s68
	s_ashr_i32 s55, s54, 31
	s_lshl_b64 s[60:61], s[54:55], 19
	s_add_u32 s60, s33, s60
	s_addc_u32 s61, s73, s61
	s_and_b64 s[64:65], s[8:9], exec
	s_cselect_b32 s55, s61, s67
	s_cselect_b32 s70, s60, s66
	s_lshl_b32 s96, s62, 8
	s_min_i32 s11, s10, 0x100
	s_ashr_i32 s97, s96, 31
	s_lshl_b32 s64, s10, 8
	s_ashr_i32 s12, s11, 3
	s_ashr_i32 s65, s64, 31
	s_lshl_b64 s[10:11], s[96:97], 2
	s_add_u32 s10, s20, s10
	s_addc_u32 s11, s84, s11
	s_mul_hi_i32 s13, s12, 0x3000
	s_mulk_i32 s12, 0x3000
	s_add_u32 s12, s10, s12
	s_addc_u32 s13, s11, s13
	s_lshl_b64 s[10:11], s[64:65], 2
	s_add_u32 s14, s85, s10
	s_addc_u32 s15, s86, s11
	s_and_b64 s[10:11], s[44:45], exec
	s_cselect_b32 s11, s15, s13
	s_cselect_b32 s10, s14, s12
	s_add_u32 s65, s66, 0x100
	s_addc_u32 s71, s67, 0
	v_lshl_add_u64 v[128:129], s[10:11], 0, v[148:149]
	s_add_u32 s10, s68, 0x40080
	v_mov_b64_e32 v[0:1], 0
	v_mov_b64_e32 v[2:3], 0
	v_mov_b64_e32 v[4:5], 0
	v_mov_b64_e32 v[6:7], 0
	v_mov_b64_e32 v[8:9], 0
	v_mov_b64_e32 v[10:11], 0
	v_mov_b64_e32 v[12:13], 0
	v_mov_b64_e32 v[14:15], 0
	v_mov_b64_e32 v[16:17], 0
	v_mov_b64_e32 v[18:19], 0
	v_mov_b64_e32 v[20:21], 0
	v_mov_b64_e32 v[22:23], 0
	v_mov_b64_e32 v[24:25], 0
	v_mov_b64_e32 v[26:27], 0
	v_mov_b64_e32 v[28:29], 0
	v_mov_b64_e32 v[30:31], 0
	v_mov_b64_e32 v[32:33], 0
	v_mov_b64_e32 v[34:35], 0
	v_mov_b64_e32 v[36:37], 0
	v_mov_b64_e32 v[38:39], 0
	v_mov_b64_e32 v[40:41], 0
	v_mov_b64_e32 v[42:43], 0
	v_mov_b64_e32 v[44:45], 0
	v_mov_b64_e32 v[46:47], 0
	v_mov_b64_e32 v[48:49], 0
	v_mov_b64_e32 v[50:51], 0
	v_mov_b64_e32 v[52:53], 0
	v_mov_b64_e32 v[54:55], 0
	v_mov_b64_e32 v[56:57], 0
	v_mov_b64_e32 v[58:59], 0
	v_mov_b64_e32 v[60:61], 0
	v_mov_b64_e32 v[62:63], 0
	v_mov_b64_e32 v[64:65], 0
	v_mov_b64_e32 v[66:67], 0
	v_mov_b64_e32 v[68:69], 0
	v_mov_b64_e32 v[70:71], 0
	v_mov_b64_e32 v[72:73], 0
	v_mov_b64_e32 v[74:75], 0
	v_mov_b64_e32 v[76:77], 0
	v_mov_b64_e32 v[78:79], 0
	v_mov_b64_e32 v[80:81], 0
	v_mov_b64_e32 v[82:83], 0
	v_mov_b64_e32 v[84:85], 0
	v_mov_b64_e32 v[86:87], 0
	v_mov_b64_e32 v[88:89], 0
	v_mov_b64_e32 v[90:91], 0
	v_mov_b64_e32 v[92:93], 0
	v_mov_b64_e32 v[94:95], 0
	v_mov_b64_e32 v[96:97], 0
	v_mov_b64_e32 v[98:99], 0
	v_mov_b64_e32 v[100:101], 0
	v_mov_b64_e32 v[102:103], 0
	v_mov_b64_e32 v[104:105], 0
	v_mov_b64_e32 v[106:107], 0
	v_mov_b64_e32 v[108:109], 0
	v_mov_b64_e32 v[110:111], 0
	v_mov_b64_e32 v[112:113], 0
	v_mov_b64_e32 v[114:115], 0
	v_mov_b64_e32 v[116:117], 0
	v_mov_b64_e32 v[118:119], 0
	v_mov_b64_e32 v[120:121], 0
	v_mov_b64_e32 v[122:123], 0
	v_mov_b64_e32 v[124:125], 0
	v_mov_b64_e32 v[126:127], 0
	s_addc_u32 s11, s69, 0
	s_mov_b32 s96, -2
	s_branch .LBB0_961

; template <class Epi, class Sched, bool ALIGN_EPI = false, bool SP2 = false>
; __device__ __forceinline__ void gemm_phase(PG8_LAS unsigned char* lds, const Gemm g, const Sched& S, const Epi& E) {
;     ...
;         const bool has_next = S.next(ui + 1, nxt);
;         const char* nA = has_next ? (const char*)g.A + (size_t)nxt.pm * tstep : cA; const char* nB = has_next ? (const char*)g.Bt + (size_t)nxt.pn * tstep : cB;
;         for (int t = 0; t < nt; t += 2) {
;             const bool last = (t == nt - 2);
;             const char* a1 = cA + (size_t)(t + 1) * kstep;
;             const char* a2 = last ? nA : cA + (size_t)(t + 2) * kstep; const char* b2 = last ? nB : cB + (size_t)(t + 2) * kstep;
;             const char* a3 = a2 + kstep; const char* b3 = b2 + kstep;
;     ...
; #pragma unroll
;         for (int a = 0; a < 2; ++a)
; #pragma unroll
;             for (int b = 0; b < 2; ++b)
; #pragma unroll
;                 for (int m = 0; m < 4; ++m)
; #pragma unroll
;                     for (int n = 0; n < 2; ++n) acc[a][b][m][n] = (f32x4){0.f, 0.f, 0.f, 0.f};
;         cur = nxt; cA = nA; cB = nB; ++ui;
.LBB0_1271:
	s_ashr_i32 s41, s40, 31
	s_lshl_b64 s[42:43], s[40:41], 19
	s_add_u32 s42, s33, s42
	s_addc_u32 s43, s56, s43
	s_and_b64 s[44:45], s[8:9], exec
	s_cselect_b32 s41, s43, s53
	s_cselect_b32 s47, s42, s52
	s_ashr_i32 s39, s38, 31
	s_lshl_b64 s[44:45], s[38:39], 19
	s_add_u32 s44, s57, s44
	s_addc_u32 s45, s58, s45
	s_and_b64 s[54:55], s[8:9], exec
	s_cselect_b32 s39, s45, s51
	s_cselect_b32 s49, s44, s50
	s_add_u32 s77, s50, 0x100
	s_addc_u32 s78, s51, 0
	s_add_u32 s50, s52, 0x40080
	v_mov_b64_e32 v[0:1], 0
	v_mov_b64_e32 v[2:3], 0
	v_mov_b64_e32 v[4:5], 0
	v_mov_b64_e32 v[6:7], 0
	v_mov_b64_e32 v[8:9], 0
	v_mov_b64_e32 v[10:11], 0
	v_mov_b64_e32 v[12:13], 0
	v_mov_b64_e32 v[14:15], 0
	v_mov_b64_e32 v[16:17], 0
	v_mov_b64_e32 v[18:19], 0
	v_mov_b64_e32 v[20:21], 0
	v_mov_b64_e32 v[22:23], 0
	v_mov_b64_e32 v[24:25], 0
	v_mov_b64_e32 v[26:27], 0
	v_mov_b64_e32 v[28:29], 0
	v_mov_b64_e32 v[30:31], 0
	v_mov_b64_e32 v[32:33], 0
	v_mov_b64_e32 v[34:35], 0
	v_mov_b64_e32 v[36:37], 0
	v_mov_b64_e32 v[38:39], 0
	v_mov_b64_e32 v[40:41], 0
	v_mov_b64_e32 v[42:43], 0
	v_mov_b64_e32 v[44:45], 0
	v_mov_b64_e32 v[46:47], 0
	v_mov_b64_e32 v[48:49], 0
	v_mov_b64_e32 v[50:51], 0
	v_mov_b64_e32 v[52:53], 0
	v_mov_b64_e32 v[54:55], 0
	v_mov_b64_e32 v[56:57], 0
	v_mov_b64_e32 v[58:59], 0
	v_mov_b64_e32 v[60:61], 0
	v_mov_b64_e32 v[62:63], 0
	v_mov_b64_e32 v[64:65], 0
	v_mov_b64_e32 v[66:67], 0
	v_mov_b64_e32 v[68:69], 0
	v_mov_b64_e32 v[70:71], 0
	v_mov_b64_e32 v[72:73], 0
	v_mov_b64_e32 v[74:75], 0
	v_mov_b64_e32 v[76:77], 0
	v_mov_b64_e32 v[78:79], 0
	v_mov_b64_e32 v[80:81], 0
	v_mov_b64_e32 v[82:83], 0
	v_mov_b64_e32 v[84:85], 0
	v_mov_b64_e32 v[86:87], 0
	v_mov_b64_e32 v[88:89], 0
	v_mov_b64_e32 v[90:91], 0
	v_mov_b64_e32 v[92:93], 0
	v_mov_b64_e32 v[94:95], 0
	v_mov_b64_e32 v[96:97], 0
	v_mov_b64_e32 v[98:99], 0
	v_mov_b64_e32 v[100:101], 0
	v_mov_b64_e32 v[102:103], 0
	v_mov_b64_e32 v[104:105], 0
	v_mov_b64_e32 v[106:107], 0
	v_mov_b64_e32 v[108:109], 0
	v_mov_b64_e32 v[110:111], 0
	v_mov_b64_e32 v[112:113], 0
	v_mov_b64_e32 v[114:115], 0
	v_mov_b64_e32 v[116:117], 0
	v_mov_b64_e32 v[118:119], 0
	v_mov_b64_e32 v[120:121], 0
	v_mov_b64_e32 v[122:123], 0
	v_mov_b64_e32 v[124:125], 0
	v_mov_b64_e32 v[126:127], 0
	s_addc_u32 s51, s53, 0
	s_mov_b32 s79, -2
	s_waitcnt lgkmcnt(0)

; #define PG8_LAS __attribute__((address_space(3)))
;     __device__ __forceinline__ void prefetch(PG8_LAS unsigned char* sp, const Unit& u, int wid, int lane) const {
;         const int seq = (u.pm < 256) ? (u.pm >> 3) : 32;
;         const float* src = (wid < 4) ? rowss + u.pm * BM + wid * 64 : bias + (size_t)seq * 5632 + u.pn * HALF + (wid < 6 ? (wid - 4) * 64 : 2816 + (wid - 6) * 64);
;         __builtin_amdgcn_global_load_lds((const unsigned*)(src + lane), (PG8_LAS unsigned*)(sp + wid * 256), 4, 0, 0);
; template <class Epi, class Sched, bool ALIGN_EPI = false, bool SP2 = false>
; __device__ __forceinline__ void gemm_phase(PG8_LAS unsigned char* lds, const Gemm g, const Sched& S, const Epi& E) {
;     ...
; #pragma unroll
;         for (int a = 0; a < 2; ++a)
; #pragma unroll
;             for (int b = 0; b < 2; ++b)
; #pragma unroll
;                 for (int m = 0; m < 4; ++m)
; #pragma unroll
;                     for (int n = 0; n < 2; ++n) acc[a][b][m][n] = (f32x4){0.f, 0.f, 0.f, 0.f};
;         cur = nxt; cA = nA; cB = nB; ++ui;
.LBB0_1357:
	s_ashr_i32 s39, s38, 31
	s_lshl_b64 s[40:41], s[38:39], 19
	s_add_u32 s40, s34, s40
	s_addc_u32 s41, s35, s41
	s_and_b64 s[42:43], s[6:7], exec
	s_cselect_b32 s39, s41, s53
	s_cselect_b32 s73, s40, s52
	s_ashr_i32 s37, s36, 31
	s_lshl_b64 s[42:43], s[36:37], 19
	s_add_u32 s42, s33, s42
	s_addc_u32 s43, s54, s43
	s_and_b64 s[46:47], s[6:7], exec
	s_cselect_b32 s37, s43, s49
	s_cselect_b32 s74, s42, s48
	s_lshl_b32 s44, s44, 7
	s_lshl_b32 s46, s50, 8
	s_ashr_i32 s14, s50, 3
	s_ashr_i32 s45, s44, 31
	s_ashr_i32 s47, s46, 31
	s_cmpk_lt_i32 s50, 0x100
	s_mul_i32 s15, s14, 0x1600
	s_mul_hi_i32 s14, s14, 0x1600
	s_cselect_b32 s51, s14, 0
	s_cselect_b32 s50, s15, 0x2c000
	s_lshl_b64 s[50:51], s[50:51], 2
	s_add_u32 s14, s62, s50
	s_addc_u32 s15, s63, s51
	s_lshl_b64 s[50:51], s[44:45], 2
	s_add_u32 s14, s14, s50
	s_addc_u32 s15, s15, s51
	s_add_u32 s14, s14, s16
	s_addc_u32 s15, s15, s17
	s_lshl_b64 s[50:51], s[46:47], 2
	s_add_u32 s45, s68, s50
	s_addc_u32 s47, s69, s51
	s_and_b64 s[50:51], s[20:21], exec
	s_cselect_b32 s51, s47, s15
	s_cselect_b32 s50, s45, s14
	s_add_u32 s45, s48, 0x100
	s_addc_u32 s47, s49, 0
	s_add_u32 s48, s52, 0x40080
	v_mov_b64_e32 v[0:1], 0
	v_mov_b64_e32 v[2:3], 0
	v_mov_b64_e32 v[4:5], 0
	v_mov_b64_e32 v[6:7], 0
	v_mov_b64_e32 v[8:9], 0
	v_mov_b64_e32 v[10:11], 0
	v_mov_b64_e32 v[12:13], 0
	v_mov_b64_e32 v[14:15], 0
	v_mov_b64_e32 v[16:17], 0
	v_mov_b64_e32 v[18:19], 0
	v_mov_b64_e32 v[20:21], 0
	v_mov_b64_e32 v[22:23], 0
	v_mov_b64_e32 v[24:25], 0
	v_mov_b64_e32 v[26:27], 0
	v_mov_b64_e32 v[28:29], 0
	v_mov_b64_e32 v[30:31], 0
	v_mov_b64_e32 v[32:33], 0
	v_mov_b64_e32 v[34:35], 0
	v_mov_b64_e32 v[36:37], 0
	v_mov_b64_e32 v[38:39], 0
	v_mov_b64_e32 v[40:41], 0
	v_mov_b64_e32 v[42:43], 0
	v_mov_b64_e32 v[44:45], 0
	v_mov_b64_e32 v[46:47], 0
	v_mov_b64_e32 v[48:49], 0
	v_mov_b64_e32 v[50:51], 0
	v_mov_b64_e32 v[52:53], 0
	v_mov_b64_e32 v[54:55], 0
	v_mov_b64_e32 v[56:57], 0
	v_mov_b64_e32 v[58:59], 0
	v_mov_b64_e32 v[60:61], 0
	v_mov_b64_e32 v[62:63], 0
	v_mov_b64_e32 v[64:65], 0
	v_mov_b64_e32 v[66:67], 0
	v_mov_b64_e32 v[68:69], 0
	v_mov_b64_e32 v[70:71], 0
	v_mov_b64_e32 v[72:73], 0
	v_mov_b64_e32 v[74:75], 0
	v_mov_b64_e32 v[76:77], 0
	v_mov_b64_e32 v[78:79], 0
	v_mov_b64_e32 v[80:81], 0
	v_mov_b64_e32 v[82:83], 0
	v_mov_b64_e32 v[84:85], 0
	v_mov_b64_e32 v[86:87], 0
	v_mov_b64_e32 v[88:89], 0
	v_mov_b64_e32 v[90:91], 0
	v_mov_b64_e32 v[92:93], 0
	v_mov_b64_e32 v[94:95], 0
	v_mov_b64_e32 v[96:97], 0
	v_mov_b64_e32 v[98:99], 0
	v_mov_b64_e32 v[100:101], 0
	v_mov_b64_e32 v[102:103], 0
	v_mov_b64_e32 v[104:105], 0
	v_mov_b64_e32 v[106:107], 0
	v_mov_b64_e32 v[108:109], 0
	v_mov_b64_e32 v[110:111], 0
	v_mov_b64_e32 v[112:113], 0
	v_mov_b64_e32 v[114:115], 0
	v_mov_b64_e32 v[132:133], 0
	v_mov_b64_e32 v[134:135], 0
	v_mov_b64_e32 v[136:137], 0
	v_mov_b64_e32 v[138:139], 0
	v_mov_b64_e32 v[140:141], 0
	v_mov_b64_e32 v[142:143], 0
	v_lshl_add_u64 v[116:117], s[50:51], 0, v[160:161]
	s_addc_u32 s49, s53, 0
	s_mov_b32 s75, -2
	s_branch .LBB0_1359

; template <class Epi, class Sched, bool ALIGN_EPI = false, bool SP2 = false>
; __device__ __forceinline__ void gemm_phase(PG8_LAS unsigned char* lds, const Gemm g, const Sched& S, const Epi& E) {
;     ...
;             const char* a1 = cA + (size_t)(t + 1) * kstep;
;             const char* a2 = last ? nA : cA + (size_t)(t + 2) * kstep; const char* b2 = last ? nB : cB + (size_t)(t + 2) * kstep;
;     ...
; #pragma unroll
;         for (int a = 0; a < 2; ++a)
; #pragma unroll
;             for (int b = 0; b < 2; ++b)
; #pragma unroll
;                 for (int m = 0; m < 4; ++m)
; #pragma unroll
;                     for (int n = 0; n < 2; ++n) acc[a][b][m][n] = (f32x4){0.f, 0.f, 0.f, 0.f};
;         cur = nxt; cA = nA; cB = nB; ++ui;
.LBB0_1431:
	s_add_u32 s50, s20, 0x100
	v_mov_b64_e32 v[0:1], 0
	v_mov_b64_e32 v[2:3], 0
	v_mov_b64_e32 v[4:5], 0
	v_mov_b64_e32 v[6:7], 0
	v_mov_b64_e32 v[8:9], 0
	v_mov_b64_e32 v[10:11], 0
	v_mov_b64_e32 v[12:13], 0
	v_mov_b64_e32 v[14:15], 0
	v_mov_b64_e32 v[16:17], 0
	v_mov_b64_e32 v[18:19], 0
	v_mov_b64_e32 v[20:21], 0
	v_mov_b64_e32 v[22:23], 0
	v_mov_b64_e32 v[24:25], 0
	v_mov_b64_e32 v[26:27], 0
	v_mov_b64_e32 v[28:29], 0
	v_mov_b64_e32 v[30:31], 0
	v_mov_b64_e32 v[32:33], 0
	v_mov_b64_e32 v[34:35], 0
	v_mov_b64_e32 v[36:37], 0
	v_mov_b64_e32 v[38:39], 0
	v_mov_b64_e32 v[40:41], 0
	v_mov_b64_e32 v[42:43], 0
	v_mov_b64_e32 v[44:45], 0
	v_mov_b64_e32 v[46:47], 0
	v_mov_b64_e32 v[48:49], 0
	v_mov_b64_e32 v[50:51], 0
	v_mov_b64_e32 v[52:53], 0
	v_mov_b64_e32 v[54:55], 0
	v_mov_b64_e32 v[56:57], 0
	v_mov_b64_e32 v[58:59], 0
	v_mov_b64_e32 v[60:61], 0
	v_mov_b64_e32 v[62:63], 0
	v_mov_b64_e32 v[64:65], 0
	v_mov_b64_e32 v[66:67], 0
	v_mov_b64_e32 v[68:69], 0
	v_mov_b64_e32 v[70:71], 0
	v_mov_b64_e32 v[72:73], 0
	v_mov_b64_e32 v[74:75], 0
	v_mov_b64_e32 v[76:77], 0
	v_mov_b64_e32 v[78:79], 0
	v_mov_b64_e32 v[80:81], 0
	v_mov_b64_e32 v[82:83], 0
	v_mov_b64_e32 v[84:85], 0
	v_mov_b64_e32 v[86:87], 0
	v_mov_b64_e32 v[88:89], 0
	v_mov_b64_e32 v[90:91], 0
	v_mov_b64_e32 v[92:93], 0
	v_mov_b64_e32 v[94:95], 0
	v_mov_b64_e32 v[96:97], 0
	v_mov_b64_e32 v[98:99], 0
	v_mov_b64_e32 v[100:101], 0
	v_mov_b64_e32 v[102:103], 0
	v_mov_b64_e32 v[104:105], 0
	v_mov_b64_e32 v[106:107], 0
	v_mov_b64_e32 v[108:109], 0
	v_mov_b64_e32 v[110:111], 0
	v_mov_b64_e32 v[112:113], 0
	v_mov_b64_e32 v[114:115], 0
	v_mov_b64_e32 v[116:117], 0
	v_mov_b64_e32 v[118:119], 0
	v_mov_b64_e32 v[120:121], 0
	v_mov_b64_e32 v[122:123], 0
	v_mov_b64_e32 v[124:125], 0
	v_mov_b64_e32 v[126:127], 0
	s_addc_u32 s51, s21, 0
	s_mov_b32 s52, -2
